# grid barrier: XCD leaders no longer bump the (now unpolled) per-XCD generation word after their acquire
# speedup vs baseline: 1.0004x; 1.0004x over previous
; DI unsigned xb_add(unsigned* p, unsigned v) { return __hip_atomic_fetch_add(p, v, __ATOMIC_RELAXED, __HIP_MEMORY_SCOPE_AGENT); }
; DI void xcd_barrier(const XcdBarrier& b) {
;     ...
;       __builtin_amdgcn_fence(__ATOMIC_ACQUIRE, "agent");
;       xb_add(&bar[XB_XGEN(b.x)], 1u);
;       asm volatile("s_waitcnt vmcnt(0)" ::: "memory");
.LBB0_103:
	s_or_b64 exec, exec, s[4:5]
	s_mov_b64 s[4:5], exec
	v_mbcnt_lo_u32_b32 v0, s4, 0
	v_mbcnt_hi_u32_b32 v0, s5, v0
	v_cmp_eq_u32_e32 vcc, 0, v0
	s_waitcnt vmcnt(0)
	buffer_inv sc1
	s_and_saveexec_b64 s[6:7], vcc
	s_cbranch_execz .LBB0_105
	s_bcnt1_i32_b64 s3, s[4:5]
	v_readlane_b32 s4, v251, 53
	v_mov_b32_e32 v0, 0
	v_mov_b32_e32 v1, s3
	v_readlane_b32 s5, v251, 54
	s_nop 4
	s_nop 0
	s_nop 0

; DI unsigned xb_add(unsigned* p, unsigned v) { return __hip_atomic_fetch_add(p, v, __ATOMIC_RELAXED, __HIP_MEMORY_SCOPE_AGENT); }
; DI void xcd_barrier(const XcdBarrier& b) {
;     ...
;       __builtin_amdgcn_fence(__ATOMIC_ACQUIRE, "agent");
;       xb_add(&bar[XB_XGEN(b.x)], 1u);
;       asm volatile("s_waitcnt vmcnt(0)" ::: "memory");
.LBB0_190:
	s_or_b64 exec, exec, s[2:3]
	s_mov_b64 s[2:3], exec
	v_mbcnt_lo_u32_b32 v0, s2, 0
	v_mbcnt_hi_u32_b32 v0, s3, v0
	v_cmp_eq_u32_e32 vcc, 0, v0
	s_waitcnt vmcnt(0)
	buffer_inv sc1
	s_and_saveexec_b64 s[4:5], vcc
	s_cbranch_execz .LBB0_192
	s_bcnt1_i32_b64 s2, s[2:3]
	v_mov_b32_e32 v0, s2
	v_readlane_b32 s2, v251, 53
	v_readlane_b32 s3, v251, 54
	s_nop 4
	s_nop 0
	s_nop 0

; DI unsigned xb_add(unsigned* p, unsigned v) { return __hip_atomic_fetch_add(p, v, __ATOMIC_RELAXED, __HIP_MEMORY_SCOPE_AGENT); }
; DI void xcd_barrier(const XcdBarrier& b) {
;     ...
;       __builtin_amdgcn_fence(__ATOMIC_ACQUIRE, "agent");
;       xb_add(&bar[XB_XGEN(b.x)], 1u);
;       asm volatile("s_waitcnt vmcnt(0)" ::: "memory");
.LBB0_520:
	s_or_b64 exec, exec, s[2:3]
	s_mov_b64 s[2:3], exec
	v_mbcnt_lo_u32_b32 v0, s2, 0
	v_mbcnt_hi_u32_b32 v0, s3, v0
	v_cmp_eq_u32_e32 vcc, 0, v0
	s_waitcnt vmcnt(0)
	buffer_inv sc1
	s_and_saveexec_b64 s[4:5], vcc
	s_cbranch_execz .LBB0_107
	s_bcnt1_i32_b64 s2, s[2:3]
	v_mov_b32_e32 v0, s2
	v_readlane_b32 s2, v251, 53
	v_readlane_b32 s3, v251, 54
	s_nop 4
	s_nop 0
	s_nop 0
	s_branch .LBB0_107
